# gla_a/gla_c: the end-of-unit barrier moved behind the next unit's first load batch (loads in flight while the workgroup synchronises)
# baseline (speedup 1.0000x reference)
.LBB0_651:
	s_lshl_b32 s0, s28, 6
	s_add_i32 s43, s13, s0
	v_add_u32_e32 v6, s43, v128
	v_mov_b64_e32 v[0:1], s[20:21]
	v_mad_i64_i32 v[2:3], s[0:1], v6, s37, v[0:1]
	v_lshl_add_u64 v[2:3], v[2:3], 0, v[30:31]
	v_add_u32_e32 v4, 16, v6
	v_add_co_u32_e32 v2, vcc, 0x1000, v2
	v_mad_i64_i32 v[4:5], s[0:1], v4, s37, v[0:1]
	s_nop 0
	v_addc_co_u32_e32 v3, vcc, 0, v3, vcc
	v_lshl_add_u64 v[4:5], v[4:5], 0, v[30:31]
	v_add_co_u32_e32 v4, vcc, 0x1000, v4
	s_and_b32 s44, s12, 3
	s_nop 0
	v_addc_co_u32_e32 v5, vcc, 0, v5, vcc
	global_load_dwordx4 v[16:19], v[2:3], off offset:1344
	global_load_dwordx4 v[12:15], v[4:5], off offset:1344
	v_add_u32_e32 v2, 32, v6
	v_mad_i64_i32 v[2:3], s[0:1], v2, s37, v[0:1]
	v_lshl_add_u64 v[2:3], v[2:3], 0, v[30:31]
	v_add_u32_e32 v4, 48, v6
	v_add_co_u32_e32 v2, vcc, 0x1000, v2
	v_mad_i64_i32 v[0:1], s[0:1], v4, s37, v[0:1]
	s_nop 0
	v_addc_co_u32_e32 v3, vcc, 0, v3, vcc
	v_lshl_add_u64 v[0:1], v[0:1], 0, v[30:31]
	v_add_co_u32_e32 v0, vcc, 0x1000, v0
	s_lshl_b32 s22, s44, 9
	s_nop 0
	v_addc_co_u32_e32 v1, vcc, 0, v1, vcc
	global_load_dwordx4 v[8:11], v[2:3], off offset:1344
	s_nop 0
	global_load_dwordx4 v[0:3], v[0:1], off offset:1344
	v_lshl_add_u64 v[24:25], v[32:33], 0, s[22:23]
	v_mov_b32_e32 v4, 0
	v_lshlrev_b32_e32 v26, 2, v34
	v_mov_b32_e32 v20, 0
	s_waitcnt lgkmcnt(0)
	v_mov_b32_e32 v21, 0
	v_mov_b32_e32 v22, 0
	v_mov_b32_e32 v23, 0
	s_lshl_b32 s98, s44, 7
	s_or_b32 s98, s98, s34
	v_or_b32_e32 v208, s98, v34
	v_mov_b32_e32 v209, v31
	v_lshl_add_u64 v[208:209], v[208:209], 2, s[90:91]
	global_load_dword v210, v[208:209], off
	global_load_dword v211, v[208:209], off offset:64
	s_and_saveexec_b64 s[0:1], s[2:3]
	v_mov_b32_e32 v27, v31
	v_lshl_add_u64 v[6:7], v[24:25], 0, v[26:27]
	v_add_co_u32_e32 v20, vcc, 0x1000, v6
	s_nop 1
	v_addc_co_u32_e32 v21, vcc, 0, v7, vcc
	v_add_co_u32_e32 v22, vcc, 0x2000, v6
	s_nop 1
	v_addc_co_u32_e32 v23, vcc, 0, v7, vcc
	v_add_co_u32_e32 v28, vcc, 0x3000, v6
	s_nop 1
	v_addc_co_u32_e32 v29, vcc, 0, v7, vcc
	global_load_dword v200, v[6:7], off offset:64
	global_load_dword v201, v[6:7], off offset:2112
	global_load_dword v202, v[20:21], off offset:64
	global_load_dword v203, v[20:21], off offset:2112
	global_load_dword v204, v[22:23], off offset:64
	global_load_dword v205, v[22:23], off offset:2112
	global_load_dword v206, v[28:29], off offset:64
	global_load_dword v207, v[28:29], off offset:2112
	global_load_dword v5, v[6:7], off
	s_nop 0
	global_load_dword v6, v[6:7], off offset:2048
	s_nop 0
	global_load_dword v7, v[20:21], off
	s_nop 0
	global_load_dword v21, v[20:21], off offset:2048
	s_nop 0
	global_load_dword v27, v[22:23], off
	s_nop 0
	global_load_dword v22, v[22:23], off offset:2048
	s_nop 0
	global_load_dword v23, v[28:29], off
	s_nop 0
	global_load_dword v28, v[28:29], off offset:2048
	s_or_b64 exec, exec, s[0:1]
	v_add_u32_e32 v230, s43, v144
	v_mov_b64_e32 v[228:229], s[20:21]
	v_mad_i64_i32 v[228:229], vcc, v230, s37, v[228:229]
	s_lshl_b32 s100, s44, 8
	s_mov_b32 s101, 0
	v_lshl_add_u64 v[228:229], v[228:229], 0, s[100:101]
	v_mov_b32_e32 v230, v40
	v_mov_b32_e32 v231, v31
	v_lshl_add_u64 v[228:229], v[228:229], 0, v[230:231]
	global_load_dwordx4 v[212:215], v[228:229], off offset:2368
	global_load_dwordx4 v[216:219], v[228:229], off offset:3392
	global_load_dwordx4 v[220:223], v[228:229], off offset:2496
	global_load_dwordx4 v[224:227], v[228:229], off offset:3520
	s_barrier
	s_waitcnt vmcnt(4)
	s_and_saveexec_b64 s[0:1], s[2:3]
	v_cvt_pk_bf16_f32 v20, v5, v6
	v_cvt_pk_bf16_f32 v21, v7, v21
	v_cvt_pk_bf16_f32 v22, v27, v22
	v_cvt_pk_bf16_f32 v23, v23, v28

.LBB0_664:
	v_add_u32_e32 v41, s0, v120
	v_add_u32_e32 v18, 0x1b800, v41
	v_add_u32_e32 v22, 0x1b840, v41
	ds_read_b128 v[18:21], v18
	ds_read_b128 v[22:25], v22
	v_add_u32_e32 v42, 0x1c100, v41
	v_add_u32_e32 v41, 0x1c140, v41
	ds_read_b128 v[42:45], v42
	ds_read_b128 v[46:49], v41
	s_waitcnt lgkmcnt(3)
	v_mfma_f32_16x16x32_bf16 v[26:29], v[0:3], v[18:21], 0
	s_addk_i32 s0, 0x1200
	s_cmpk_lg_i32 s0, 0x4800
	v_mfma_f32_16x16x32_bf16 v[18:21], v[8:11], v[18:21], 0
	s_waitcnt lgkmcnt(1)
	v_mfma_f32_16x16x32_bf16 v[50:53], v[0:3], v[42:45], 0
	v_mfma_f32_16x16x32_bf16 v[42:45], v[8:11], v[42:45], 0
	v_mfma_f32_16x16x32_bf16 v[26:29], v[4:7], v[22:25], v[26:29]
	v_mfma_f32_16x16x32_bf16 v[18:21], v[12:15], v[22:25], v[18:21]
	s_waitcnt lgkmcnt(0)
	v_mfma_f32_16x16x32_bf16 v[22:25], v[4:7], v[46:49], v[50:53]
	s_nop 4
	v_cvt_pk_bf16_f32 v26, v26, v27
	v_cvt_pk_bf16_f32 v27, v28, v29
	v_cvt_pk_bf16_f32 v28, v18, v19
	v_mfma_f32_16x16x32_bf16 v[42:45], v[12:15], v[46:49], v[42:45]
	v_cvt_pk_bf16_f32 v29, v20, v21
	v_cvt_pk_bf16_f32 v20, v22, v23
	v_cvt_pk_bf16_f32 v21, v24, v25
	s_nop 4
	v_cvt_pk_bf16_f32 v22, v42, v43
	v_cvt_pk_bf16_f32 v23, v44, v45
	v_permlane16_swap_b32_e32 v26, v28
	v_permlane16_swap_b32_e32 v27, v29
	s_nop 0
	v_permlane16_swap_b32_e32 v20, v22
	v_permlane16_swap_b32_e32 v21, v23
	global_store_dwordx4 v[16:17], v[26:29], off offset:-4096
	global_store_dwordx4 v[16:17], v[20:23], off
	v_lshl_add_u64 v[16:17], v[16:17], 0, s[24:25]
	s_cbranch_scc1 .LBB0_664
	s_add_i32 s30, s30, s72
	s_cmpk_lt_i32 s30, 0x880
	s_cbranch_scc1 .LBB0_647
	s_barrier

.LBB0_819:
	s_or_b64 exec, exec, s[0:1]
	v_or_b32_e32 v16, s44, v97
	v_mov_b64_e32 v[18:19], s[68:69]
	v_mad_i64_i32 v[18:19], s[0:1], v16, s79, v[18:19]
	v_lshl_add_u64 v[18:19], v[18:19], 0, s[70:71]
	v_lshl_add_u64 v[20:21], v[18:19], 0, s[76:77]
	v_mov_b32_e32 v230, v52
	v_mov_b32_e32 v231, v31
	v_lshl_add_u64 v[230:231], v[20:21], 0, v[230:231]
	v_mov_b32_e32 v51, v31
	v_lshl_add_u64 v[24:25], v[20:21], 0, v[50:51]
	s_waitcnt lgkmcnt(0)
	s_barrier
	v_mov_b32_e32 v54, v176
	v_mov_b32_e32 v55, v177
	ds_read2st64_b32 v[18:19], v100 offset0:108 offset1:109
	v_ashrrev_i32_e32 v17, 31, v16
	v_lshlrev_b64 v[16:17], 10, v[16:17]
	v_lshl_add_u64 v[16:17], s[72:73], 0, v[16:17]
	v_lshl_add_u64 v[16:17], v[16:17], 0, s[70:71]
	s_waitcnt lgkmcnt(0)
	v_add_f32_e32 v18, v18, v19
	v_fmamk_f32 v18, v18, 0x3c000000, v109
	v_rsq_f32_e32 v18, v18
	v_lshl_add_u64 v[22:23], v[16:17], 0, v[50:51]
	v_mov_b32_e32 v56, v178
	v_mov_b32_e32 v57, v179
	v_mov_b32_e32 v24, v180
	v_mov_b32_e32 v25, v181
	v_mov_b32_e32 v228, v182
	v_mov_b32_e32 v229, v183
	v_pk_mul_f32 v[12:13], v[12:13], v[18:19] op_sel_hi:[1,0]
	v_pk_mul_f32 v[14:15], v[14:15], v[18:19] op_sel_hi:[1,0]
	v_lshlrev_b32_e32 v58, 16, v54
	v_and_b32_e32 v59, 0xffff0000, v54
	v_mul_f32_e32 v19, 0xbfb8aa3b, v58
	v_mul_f32_e32 v49, 0xbfb8aa3b, v59
	v_lshlrev_b32_e32 v54, 16, v55
	v_and_b32_e32 v55, 0xffff0000, v55
	v_exp_f32_e32 v60, v19
	v_exp_f32_e32 v61, v49
	v_mul_f32_e32 v51, 0xbfb8aa3b, v54
	v_mul_f32_e32 v53, 0xbfb8aa3b, v55
	v_exp_f32_e32 v62, v51
	v_exp_f32_e32 v63, v53
	v_pk_mul_f32 v[12:13], v[212:213], v[12:13]
	v_pk_add_f32 v[26:27], v[60:61], 1.0 op_sel_hi:[1,0]
	v_pk_mul_f32 v[14:15], v[214:215], v[14:15]
	v_pk_add_f32 v[28:29], v[62:63], 1.0 op_sel_hi:[1,0]
	s_mov_b64 vcc, s[0:1]
	v_rcp_f32_e32 v27, v27
	s_mov_b64 vcc, s[46:47]
	v_rcp_f32_e32 v26, v26
	s_mov_b64 vcc, s[48:49]
	v_rcp_f32_e32 v29, v29
	v_pk_mul_f32 v[26:27], v[26:27], v[58:59]
	v_rcp_f32_e32 v28, v28
	v_pk_mul_f32 v[12:13], v[12:13], v[26:27]
	v_pk_mul_f32 v[26:27], v[28:29], v[54:55]
	v_cvt_pk_bf16_f32 v12, v12, v13
	v_pk_mul_f32 v[14:15], v[14:15], v[26:27]
	v_lshlrev_b32_e32 v26, 16, v56
	v_cvt_pk_bf16_f32 v13, v14, v15
	global_store_dwordx2 v[22:23], v[12:13], off
	v_and_b32_e32 v27, 0xffff0000, v56
	v_mul_f32_e32 v19, 0xbfb8aa3b, v26
	v_mul_f32_e32 v49, 0xbfb8aa3b, v27
	v_lshlrev_b32_e32 v28, 16, v57
	v_and_b32_e32 v29, 0xffff0000, v57
	v_exp_f32_e32 v54, v19
	v_exp_f32_e32 v55, v49
	v_mul_f32_e32 v51, 0xbfb8aa3b, v28
	v_mul_f32_e32 v53, 0xbfb8aa3b, v29
	v_exp_f32_e32 v56, v51
	v_exp_f32_e32 v57, v53
	v_pk_add_f32 v[54:55], v[54:55], 1.0 op_sel_hi:[1,0]
	v_pk_mul_f32 v[8:9], v[8:9], v[18:19] op_sel_hi:[1,0]
	v_pk_mul_f32 v[10:11], v[10:11], v[18:19] op_sel_hi:[1,0]
	v_pk_add_f32 v[56:57], v[56:57], 1.0 op_sel_hi:[1,0]
	s_mov_b64 vcc, s[0:1]
	v_rcp_f32_e32 v55, v55
	s_mov_b64 vcc, s[46:47]
	v_rcp_f32_e32 v54, v54
	s_mov_b64 vcc, s[48:49]
	v_pk_mul_f32 v[26:27], v[54:55], v[26:27]
	v_rcp_f32_e32 v55, v57
	s_nop 0
	v_rcp_f32_e32 v54, v56
	s_nop 0
	v_pk_mul_f32 v[28:29], v[54:55], v[28:29]
	v_mov_b32_e32 v53, v31
	v_pk_mul_f32 v[8:9], v[216:217], v[8:9]
	v_pk_mul_f32 v[10:11], v[218:219], v[10:11]
	v_pk_mul_f32 v[8:9], v[8:9], v[26:27]
	v_pk_mul_f32 v[10:11], v[10:11], v[28:29]
	v_cvt_pk_bf16_f32 v8, v8, v9
	v_cvt_pk_bf16_f32 v9, v10, v11
	global_store_dwordx2 v[22:23], v[8:9], off offset:32
	v_lshlrev_b32_e32 v14, 16, v24
	v_and_b32_e32 v15, 0xffff0000, v24
	v_lshl_add_u64 v[12:13], v[20:21], 0, v[52:53]
	v_lshlrev_b32_e32 v20, 16, v25
	v_and_b32_e32 v21, 0xffff0000, v25
	v_mul_f32_e32 v19, 0xbfb8aa3b, v14
	v_mul_f32_e32 v25, 0xbfb8aa3b, v15
	v_exp_f32_e32 v24, v19
	v_exp_f32_e32 v25, v25
	v_mul_f32_e32 v26, 0xbfb8aa3b, v20
	v_mul_f32_e32 v27, 0xbfb8aa3b, v21
	v_exp_f32_e32 v26, v26
	v_exp_f32_e32 v27, v27
	v_pk_add_f32 v[24:25], v[24:25], 1.0 op_sel_hi:[1,0]
	v_pk_mul_f32 v[4:5], v[4:5], v[18:19] op_sel_hi:[1,0]
	v_pk_mul_f32 v[6:7], v[6:7], v[18:19] op_sel_hi:[1,0]
	v_pk_add_f32 v[26:27], v[26:27], 1.0 op_sel_hi:[1,0]
	v_div_scale_f32 v55, s[44:45], v26, v26, 1.0
	v_rcp_f32_e32 v60, v55
	s_nop 0
	v_fma_f32 v64, -v55, v60, 1.0
	v_div_scale_f32 v56, s[48:49], 1.0, v26, 1.0
	v_fmac_f32_e32 v60, v64, v60
	v_mul_f32_e32 v64, v56, v60
	v_fma_f32 v68, -v55, v64, v56
	s_mov_b64 vcc, s[0:1]
	v_fmac_f32_e32 v64, v68, v60
	v_rcp_f32_e32 v25, v25
	s_mov_b64 vcc, s[46:47]
	v_fma_f32 v49, -v55, v64, v56
	v_rcp_f32_e32 v24, v24
	s_mov_b64 vcc, s[48:49]
	v_pk_mul_f32 v[14:15], v[24:25], v[14:15]
	v_rcp_f32_e32 v25, v27
	v_div_fmas_f32 v19, v49, v60, v64
	v_div_fixup_f32 v24, v19, v26, 1.0
	v_pk_mul_f32 v[20:21], v[24:25], v[20:21]
	v_readlane_b32 s0, v244, 4
	v_pk_mul_f32 v[0:1], v[0:1], v[18:19] op_sel_hi:[1,0]
	v_readlane_b32 s1, v244, 5
	s_add_i32 s84, s84, s0
	v_pk_mul_f32 v[2:3], v[2:3], v[18:19] op_sel_hi:[1,0]
	v_pk_mul_f32 v[4:5], v[4:5], v[220:221]
	v_pk_mul_f32 v[6:7], v[6:7], v[222:223]
	v_pk_mul_f32 v[4:5], v[4:5], v[14:15]
	v_pk_mul_f32 v[6:7], v[6:7], v[20:21]
	v_cvt_pk_bf16_f32 v4, v4, v5
	v_cvt_pk_bf16_f32 v5, v6, v7
	global_store_dwordx2 v[22:23], v[4:5], off offset:64
	v_lshl_add_u64 v[10:11], v[16:17], 0, v[52:53]
	s_cmpk_gt_i32 s84, 0x7ff
	v_lshlrev_b32_e32 v12, 16, v228
	v_and_b32_e32 v13, 0xffff0000, v228
	v_mul_f32_e32 v14, 0xbfb8aa3b, v12
	v_mul_f32_e32 v15, 0xbfb8aa3b, v13
	v_lshlrev_b32_e32 v8, 16, v229
	v_and_b32_e32 v9, 0xffff0000, v229
	v_exp_f32_e32 v14, v14
	v_exp_f32_e32 v15, v15
	v_mul_f32_e32 v16, 0xbfb8aa3b, v8
	v_mul_f32_e32 v17, 0xbfb8aa3b, v9
	v_exp_f32_e32 v16, v16
	v_exp_f32_e32 v17, v17
	v_pk_mul_f32 v[0:1], v[0:1], v[224:225]
	v_pk_add_f32 v[4:5], v[14:15], 1.0 op_sel_hi:[1,0]
	v_pk_mul_f32 v[2:3], v[2:3], v[226:227]
	v_pk_add_f32 v[6:7], v[16:17], 1.0 op_sel_hi:[1,0]
	s_mov_b64 vcc, s[0:1]
	v_rcp_f32_e32 v5, v5
	s_mov_b64 vcc, s[46:47]
	v_rcp_f32_e32 v4, v4
	s_mov_b64 vcc, s[48:49]
	v_pk_mul_f32 v[4:5], v[4:5], v[12:13]
	v_rcp_f32_e32 v7, v7
	s_nop 0
	v_rcp_f32_e32 v6, v6
	v_pk_mul_f32 v[0:1], v[0:1], v[4:5]
	v_pk_mul_f32 v[4:5], v[6:7], v[8:9]
	v_cvt_pk_bf16_f32 v0, v0, v1
	v_pk_mul_f32 v[2:3], v[2:3], v[4:5]
	s_nop 0
	v_cvt_pk_bf16_f32 v1, v2, v3
	global_store_dwordx2 v[10:11], v[0:1], off
	s_cbranch_scc1 .Lglc_exit
.LBB0_820:
	s_ashr_i32 s85, s84, 8
	s_and_b32 s45, s84, 63
	s_lshl_b32 s0, s85, 12
	s_lshl_b32 s1, s45, 6
	s_or_b32 s44, s0, s1
	v_or_b32_e32 v6, s44, v84
	v_mov_b64_e32 v[0:1], s[68:69]
	v_mad_i64_i32 v[2:3], s[0:1], v6, s79, v[0:1]
	v_lshl_add_u64 v[2:3], v[2:3], 0, v[30:31]
	v_or_b32_e32 v4, 16, v6
	v_add_co_u32_e32 v2, vcc, 0x1000, v2
	v_mad_i64_i32 v[4:5], s[0:1], v4, s79, v[0:1]
	s_nop 0
	v_addc_co_u32_e32 v3, vcc, 0, v3, vcc
	v_lshl_add_u64 v[4:5], v[4:5], 0, v[30:31]
	v_add_co_u32_e32 v4, vcc, 0x1000, v4
	s_bfe_u32 s86, s84, 0x20006
	s_nop 0
	v_addc_co_u32_e32 v5, vcc, 0, v5, vcc
	global_load_dwordx4 v[12:15], v[2:3], off offset:1344
	global_load_dwordx4 v[8:11], v[4:5], off offset:1344
	v_or_b32_e32 v2, 32, v6
	v_mad_i64_i32 v[2:3], s[0:1], v2, s79, v[0:1]
	v_lshl_add_u64 v[2:3], v[2:3], 0, v[30:31]
	v_or_b32_e32 v4, 48, v6
	v_add_co_u32_e32 v2, vcc, 0x1000, v2
	v_mad_i64_i32 v[0:1], s[0:1], v4, s79, v[0:1]
	s_nop 0
	v_addc_co_u32_e32 v3, vcc, 0, v3, vcc
	v_lshl_add_u64 v[0:1], v[0:1], 0, v[30:31]
	v_add_co_u32_e32 v0, vcc, 0x1000, v0
	s_lshl_b32 s70, s86, 9
	s_nop 0
	v_addc_co_u32_e32 v1, vcc, 0, v1, vcc
	global_load_dwordx4 v[4:7], v[2:3], off offset:1344
	s_nop 0
	global_load_dwordx4 v[0:3], v[0:1], off offset:1344
	v_lshl_add_u64 v[20:21], v[32:33], 0, s[70:71]
	v_lshlrev_b32_e32 v22, 2, v34
	v_mov_b32_e32 v16, 0
	v_mov_b32_e32 v17, 0
	v_mov_b32_e32 v18, 0
	v_mov_b32_e32 v19, 0
	s_lshl_b32 s98, s86, 7
	s_or_b32 s98, s98, s78
	v_or_b32_e32 v208, s98, v34
	v_mov_b32_e32 v209, v31
	v_lshl_add_u64 v[208:209], v[208:209], 2, s[90:91]
	global_load_dword v210, v[208:209], off
	global_load_dword v211, v[208:209], off offset:64
	s_and_saveexec_b64 s[0:1], s[2:3]
	v_mov_b32_e32 v23, v31
	v_lshl_add_u64 v[16:17], v[20:21], 0, v[22:23]
	v_add_co_u32_e32 v18, vcc, 0x1000, v16
	s_nop 1
	v_addc_co_u32_e32 v19, vcc, 0, v17, vcc
	v_add_co_u32_e32 v24, vcc, 0x2000, v16
	s_nop 1
	v_addc_co_u32_e32 v25, vcc, 0, v17, vcc
	v_add_co_u32_e32 v26, vcc, 0x3000, v16
	s_nop 1
	v_addc_co_u32_e32 v27, vcc, 0, v17, vcc
	global_load_dword v200, v[16:17], off offset:64
	global_load_dword v201, v[16:17], off offset:2112
	global_load_dword v202, v[18:19], off offset:64
	global_load_dword v203, v[18:19], off offset:2112
	global_load_dword v204, v[24:25], off offset:64
	global_load_dword v205, v[24:25], off offset:2112
	global_load_dword v206, v[26:27], off offset:64
	global_load_dword v207, v[26:27], off offset:2112
	global_load_dword v23, v[16:17], off
	s_nop 0
	global_load_dword v16, v[16:17], off offset:2048
	s_nop 0
	global_load_dword v17, v[18:19], off
	s_nop 0
	global_load_dword v18, v[18:19], off offset:2048
	s_nop 0
	global_load_dword v19, v[24:25], off
	s_nop 0
	global_load_dword v24, v[24:25], off offset:2048
	s_nop 0
	global_load_dword v25, v[26:27], off
	s_nop 0
	global_load_dword v26, v[26:27], off offset:2048
	s_or_b64 exec, exec, s[0:1]
	v_or_b32_e32 v190, s44, v144
	v_mov_b64_e32 v[174:175], s[68:69]
	v_mad_i64_i32 v[174:175], vcc, v190, s79, v[174:175]
	s_lshl_b32 s100, s86, 8
	s_mov_b32 s101, 0
	v_lshl_add_u64 v[174:175], v[174:175], 0, s[100:101]
	v_mov_b32_e32 v190, v48
	v_mov_b32_e32 v191, v31
	v_lshl_add_u64 v[174:175], v[174:175], 0, v[190:191]
	global_load_dwordx4 v[150:153], v[174:175], off offset:1344
	global_load_dwordx4 v[154:157], v[174:175], off offset:2368
	global_load_dwordx4 v[158:161], v[174:175], off offset:1472
	global_load_dwordx4 v[162:165], v[174:175], off offset:2496
	global_load_dwordx4 v[166:169], v[174:175], off offset:3392
	global_load_dwordx4 v[170:173], v[174:175], off offset:3520
	v_or_b32_e32 v190, s44, v97
	v_mov_b64_e32 v[186:187], s[68:69]
	v_mad_i64_i32 v[186:187], vcc, v190, s79, v[186:187]
	v_lshl_add_u64 v[186:187], v[186:187], 0, s[100:101]
	v_lshl_add_u64 v[186:187], v[186:187], 0, s[76:77]
	v_mov_b32_e32 v190, v50
	v_lshl_add_u64 v[188:189], v[186:187], 0, v[190:191]
	v_mov_b32_e32 v190, v52
	v_lshl_add_u64 v[186:187], v[186:187], 0, v[190:191]
	global_load_dwordx2 v[176:177], v[188:189], off
	global_load_dwordx2 v[178:179], v[188:189], off offset:32
	global_load_dwordx2 v[180:181], v[188:189], off offset:64
	global_load_dwordx2 v[182:183], v[186:187], off
	s_lshl_b32 s98, s85, 3
	s_lshl_b32 s99, s86, 1
	s_or_b32 s98, s99, s98
	s_ashr_i32 s99, s98, 31
	s_lshl_b64 s[98:99], s[98:99], 21
	s_add_u32 s98, s98, s52
	s_addc_u32 s99, s99, s53
	s_lshl_b32 s100, s45, 15
	s_add_u32 s98, s98, s100
	s_addc_u32 s99, s99, 0
	v_readlane_b32 s100, v244, 25
	v_lshrrev_b32_e32 v190, 4, v144
	v_and_b32_e32 v191, 15, v144
	v_lshl_add_u32 v190, s100, 4, v190
	v_lshlrev_b32_e32 v190, 8, v190
	v_lshl_add_u32 v190, v191, 4, v190
	global_load_dwordx4 v[192:195], v190, s[98:99]
	global_load_dwordx4 v[196:199], v190, s[98:99] offset:1024
	global_load_dwordx4 v[232:235], v190, s[98:99] offset:2048
	global_load_dwordx4 v[236:239], v190, s[98:99] offset:3072
	s_barrier
	s_waitcnt vmcnt(14)
	s_and_saveexec_b64 s[0:1], s[2:3]
	v_cvt_pk_bf16_f32 v16, v23, v16
	v_cvt_pk_bf16_f32 v17, v17, v18
	v_cvt_pk_bf16_f32 v18, v19, v24
	v_cvt_pk_bf16_f32 v19, v25, v26

.Lglc_exit:
	s_barrier
